# P0 weight transposes: the 4 serialized load->vmcnt(0)->ds_write round trips per tile issued together into distinct VGPRs with counted vmcnt(3..0)
# speedup vs baseline: 1.2394x; 1.0017x over previous
; DI void transpose_items(const float* src, int ld, int ncols, u16* dst, int bid, int nb, float* tile) {
;     ...
;   for (int it = bid; it < nitems; it += nb) {
;     const int k0 = (it / ntn) * 64, n0 = (it % ntn) * 64;
;     __syncthreads();
; #pragma unroll
;     for (int i = 0; i < 4; i++) {
;       int r = (tid >> 4) + 16 * i, c = (tid & 15) * 4;
;       const f32x4 v = __builtin_nontemporal_load((const f32x4*)(src + (size_t)(k0 + r) * ld + n0 + c));
;       tile[r * 65 + c] = v[0]; tile[r * 65 + c + 1] = v[1]; tile[r * 65 + c + 2] = v[2]; tile[r * 65 + c + 3] = v[3];
;     }
;     __syncthreads();
; #pragma unroll
;     for (int i = 0; i < 2; i++) {
;       int n = (tid >> 3) + 32 * i, kc = (tid & 7) * 8;
;       float f[8];
; #pragma unroll
;       for (int e = 0; e < 8; e++) f[e] = tile[(kc + e) * 65 + n];
;       *(u32x4*)(dst + (size_t)(n0 + n) * 1024 + k0 + kc) = pack8(f);
;     }
.LBB0_32:
	s_mul_hi_i32 s0, s8, 0x92492493
	s_add_i32 s0, s0, s8
	s_lshr_b32 s1, s0, 31
	s_ashr_i32 s0, s0, 5
	s_add_i32 s0, s0, s1
	s_lshl_b32 s4, s0, 6
	s_mulk_i32 s0, 0xf200
	s_add_i32 s0, s3, s0
	s_ashr_i32 s1, s0, 31
	v_lshl_add_u64 v[22:23], s[0:1], 2, v[2:3]
	v_or_b32_e32 v25, s4, v1
	v_mad_i64_i32 v[26:27], s[10:11], v25, s7, v[22:23]
	s_barrier
	global_load_dwordx4 v[26:29], v[26:27], off nt
	v_add_u32_e32 v25, s4, v9
	v_add_u32_e32 v46, s0, v6
	s_ashr_i32 s5, s4, 31
	v_ashrrev_i32_e32 v47, 31, v46
	v_lshlrev_b64 v[48:49], 11, v[46:47]
	s_add_i32 s8, s8, s16
	s_add_i32 s3, s3, s6
	s_cmpk_lt_i32 s8, 0x380
	v_mad_i64_i32 v[136:137], s[10:11], v25, s7, v[22:23]
	global_load_dwordx4 v[136:139], v[136:137], off nt
	v_add_u32_e32 v25, s4, v10
	v_mad_i64_i32 v[140:141], s[10:11], v25, s7, v[22:23]
	global_load_dwordx4 v[140:143], v[140:141], off nt
	v_add_u32_e32 v25, s4, v11
	v_mad_i64_i32 v[22:23], s[10:11], v25, s7, v[22:23]
	global_load_dwordx4 v[144:147], v[22:23], off nt
	v_lshl_add_u64 v[22:23], s[4:5], 1, v[4:5]
	v_lshl_add_u64 v[48:49], v[22:23], 0, v[48:49]
	s_waitcnt vmcnt(3)
	ds_write2_b32 v12, v26, v27 offset0:64 offset1:65
	ds_write2_b32 v12, v28, v29 offset0:66 offset1:67
	s_waitcnt vmcnt(2)
	ds_write2_b32 v13, v136, v137 offset1:1
	ds_write2_b32 v14, v138, v139 offset1:1
	s_waitcnt vmcnt(1)
	ds_write2_b32 v15, v140, v141 offset1:1
	ds_write2_b32 v16, v142, v143 offset1:1
	s_waitcnt vmcnt(0)
	ds_write2_b32 v17, v144, v145 offset1:1
	ds_write2_b32 v18, v146, v147 offset1:1
	s_waitcnt lgkmcnt(0)
	s_barrier
	ds_read2_b32 v[30:31], v19 offset0:64 offset1:96
	ds_read2_b32 v[32:33], v19 offset0:129 offset1:161
	ds_read2_b32 v[34:35], v19 offset0:194 offset1:226
	ds_read2_b32 v[36:37], v20 offset0:3 offset1:35
	ds_read2_b32 v[38:39], v20 offset0:68 offset1:100
	ds_read2_b32 v[40:41], v20 offset0:133 offset1:165
	ds_read2_b32 v[42:43], v20 offset0:198 offset1:230
	ds_read2_b32 v[44:45], v21 offset0:7 offset1:39
	s_waitcnt lgkmcnt(6)
	v_cvt_pk_bf16_f32 v26, v30, v32
	s_waitcnt lgkmcnt(4)
	v_cvt_pk_bf16_f32 v27, v34, v36
	s_waitcnt lgkmcnt(2)
	v_cvt_pk_bf16_f32 v28, v38, v40
	v_add_u32_e32 v30, 32, v46
	s_waitcnt lgkmcnt(0)
	v_cvt_pk_bf16_f32 v29, v42, v44
	global_store_dwordx4 v[48:49], v[26:29], off
	s_nop 1
	v_cvt_pk_bf16_f32 v26, v31, v33
	v_ashrrev_i32_e32 v31, 31, v30
	v_lshlrev_b64 v[30:31], 11, v[30:31]
	v_cvt_pk_bf16_f32 v27, v35, v37
	v_cvt_pk_bf16_f32 v28, v39, v41
	v_cvt_pk_bf16_f32 v29, v43, v45
	v_lshl_add_u64 v[22:23], v[22:23], 0, v[30:31]
	global_store_dwordx4 v[22:23], v[26:29], off
	s_cbranch_scc1 .LBB0_32

; DI void transpose_items(const float* src, int ld, int ncols, u16* dst, int bid, int nb, float* tile) {
;     ...
;   for (int it = bid; it < nitems; it += nb) {
;     const int k0 = (it / ntn) * 64, n0 = (it % ntn) * 64;
;     __syncthreads();
; #pragma unroll
;     for (int i = 0; i < 4; i++) {
;       int r = (tid >> 4) + 16 * i, c = (tid & 15) * 4;
;       const f32x4 v = __builtin_nontemporal_load((const f32x4*)(src + (size_t)(k0 + r) * ld + n0 + c));
;       tile[r * 65 + c] = v[0]; tile[r * 65 + c + 1] = v[1]; tile[r * 65 + c + 2] = v[2]; tile[r * 65 + c + 3] = v[3];
;     }
;     __syncthreads();
; #pragma unroll
;     for (int i = 0; i < 2; i++) {
;       int n = (tid >> 3) + 32 * i, kc = (tid & 7) * 8;
;       float f[8];
; #pragma unroll
;       for (int e = 0; e < 8; e++) f[e] = tile[(kc + e) * 65 + n];
;       *(u32x4*)(dst + (size_t)(n0 + n) * 1024 + k0 + kc) = pack8(f);
;     }
.LBB0_35:
	s_ashr_i32 s0, s7, 31
	s_lshr_b32 s0, s0, 28
	s_add_i32 s0, s7, s0
	s_ashr_i32 s0, s0, 4
	s_lshl_b32 s4, s0, 6
	s_lshl_b32 s0, s0, 10
	s_sub_i32 s0, s3, s0
	v_or_b32_e32 v26, s4, v1
	s_ashr_i32 s1, s0, 31
	v_ashrrev_i32_e32 v27, 31, v26
	v_lshl_add_u64 v[22:23], s[0:1], 2, v[2:3]
	v_lshlrev_b64 v[26:27], 12, v[26:27]
	v_lshl_add_u64 v[26:27], v[22:23], 0, v[26:27]
	s_barrier
	global_load_dwordx4 v[26:29], v[26:27], off nt
	v_add_u32_e32 v46, s0, v6
	s_ashr_i32 s5, s4, 31
	v_ashrrev_i32_e32 v47, 31, v46
	v_lshlrev_b64 v[48:49], 11, v[46:47]
	s_add_i32 s7, s7, s8
	s_add_i32 s3, s3, s6
	s_cmpk_lt_i32 s7, 0x100
	v_add_u32_e32 v136, s4, v9
	v_ashrrev_i32_e32 v137, 31, v136
	v_lshlrev_b64 v[136:137], 12, v[136:137]
	v_lshl_add_u64 v[136:137], v[22:23], 0, v[136:137]
	global_load_dwordx4 v[136:139], v[136:137], off nt
	v_add_u32_e32 v140, s4, v10
	v_ashrrev_i32_e32 v141, 31, v140
	v_lshlrev_b64 v[140:141], 12, v[140:141]
	v_lshl_add_u64 v[140:141], v[22:23], 0, v[140:141]
	global_load_dwordx4 v[140:143], v[140:141], off nt
	v_add_u32_e32 v144, s4, v11
	v_ashrrev_i32_e32 v145, 31, v144
	v_lshlrev_b64 v[144:145], 12, v[144:145]
	v_lshl_add_u64 v[22:23], v[22:23], 0, v[144:145]
	global_load_dwordx4 v[144:147], v[22:23], off nt
	v_lshl_add_u64 v[22:23], s[4:5], 1, v[4:5]
	v_lshl_add_u64 v[48:49], v[22:23], 0, v[48:49]
	s_waitcnt vmcnt(3)
	ds_write2_b32 v12, v26, v27 offset0:64 offset1:65
	ds_write2_b32 v12, v28, v29 offset0:66 offset1:67
	s_waitcnt vmcnt(2)
	ds_write2_b32 v13, v136, v137 offset1:1
	ds_write2_b32 v14, v138, v139 offset1:1
	s_waitcnt vmcnt(1)
	ds_write2_b32 v15, v140, v141 offset1:1
	ds_write2_b32 v16, v142, v143 offset1:1
	s_waitcnt vmcnt(0)
	ds_write2_b32 v17, v144, v145 offset1:1
	ds_write2_b32 v18, v146, v147 offset1:1
	s_waitcnt lgkmcnt(0)
	s_barrier
	ds_read2_b32 v[30:31], v19 offset0:64 offset1:96
	ds_read2_b32 v[32:33], v19 offset0:129 offset1:161
	ds_read2_b32 v[34:35], v19 offset0:194 offset1:226
	ds_read2_b32 v[36:37], v20 offset0:3 offset1:35
	ds_read2_b32 v[38:39], v20 offset0:68 offset1:100
	ds_read2_b32 v[40:41], v20 offset0:133 offset1:165
	ds_read2_b32 v[42:43], v20 offset0:198 offset1:230
	ds_read2_b32 v[44:45], v21 offset0:7 offset1:39
	s_waitcnt lgkmcnt(6)
	v_cvt_pk_bf16_f32 v26, v30, v32
	s_waitcnt lgkmcnt(4)
	v_cvt_pk_bf16_f32 v27, v34, v36
	s_waitcnt lgkmcnt(2)
	v_cvt_pk_bf16_f32 v28, v38, v40
	v_add_u32_e32 v30, 32, v46
	s_waitcnt lgkmcnt(0)
	v_cvt_pk_bf16_f32 v29, v42, v44
	global_store_dwordx4 v[48:49], v[26:29], off
	s_nop 1
	v_cvt_pk_bf16_f32 v26, v31, v33
	v_ashrrev_i32_e32 v31, 31, v30
	v_lshlrev_b64 v[30:31], 11, v[30:31]
	v_cvt_pk_bf16_f32 v27, v35, v37
	v_cvt_pk_bf16_f32 v28, v39, v41
	v_cvt_pk_bf16_f32 v29, v43, v45
	v_lshl_add_u64 v[22:23], v[22:23], 0, v[30:31]
	global_store_dwordx4 v[22:23], v[26:29], off
	s_cbranch_scc1 .LBB0_35

; DI void transpose_items(const float* src, int ld, int ncols, u16* dst, int bid, int nb, float* tile) {
;     ...
;   for (int it = bid; it < nitems; it += nb) {
;     const int k0 = (it / ntn) * 64, n0 = (it % ntn) * 64;
;     __syncthreads();
; #pragma unroll
;     for (int i = 0; i < 4; i++) {
;       int r = (tid >> 4) + 16 * i, c = (tid & 15) * 4;
;       const f32x4 v = __builtin_nontemporal_load((const f32x4*)(src + (size_t)(k0 + r) * ld + n0 + c));
;       tile[r * 65 + c] = v[0]; tile[r * 65 + c + 1] = v[1]; tile[r * 65 + c + 2] = v[2]; tile[r * 65 + c + 3] = v[3];
;     }
;     __syncthreads();
; #pragma unroll
;     for (int i = 0; i < 2; i++) {
;       int n = (tid >> 3) + 32 * i, kc = (tid & 7) * 8;
;       float f[8];
; #pragma unroll
;       for (int e = 0; e < 8; e++) f[e] = tile[(kc + e) * 65 + n];
;       *(u32x4*)(dst + (size_t)(n0 + n) * 1024 + k0 + kc) = pack8(f);
;     }
.LBB0_38:
	s_ashr_i32 s0, s7, 31
	s_lshr_b32 s0, s0, 27
	s_add_i32 s0, s7, s0
	s_ashr_i32 s0, s0, 5
	s_lshl_b32 s4, s0, 6
	s_lshl_b32 s0, s0, 11
	s_sub_i32 s0, s3, s0
	v_or_b32_e32 v20, s4, v1
	s_ashr_i32 s1, s0, 31
	v_ashrrev_i32_e32 v21, 31, v20
	v_lshl_add_u64 v[26:27], s[0:1], 2, v[2:3]
	v_lshlrev_b64 v[20:21], 13, v[20:21]
	v_lshl_add_u64 v[20:21], v[26:27], 0, v[20:21]
	s_barrier
	global_load_dwordx4 v[20:23], v[20:21], off nt
	v_add_u32_e32 v44, s0, v6
	s_ashr_i32 s5, s4, 31
	v_ashrrev_i32_e32 v45, 31, v44
	v_lshlrev_b64 v[46:47], 11, v[44:45]
	s_add_i32 s7, s7, s8
	s_add_i32 s3, s3, s6
	s_cmpk_lt_i32 s7, 0x200
	v_add_u32_e32 v136, s4, v7
	v_ashrrev_i32_e32 v137, 31, v136
	v_lshlrev_b64 v[136:137], 13, v[136:137]
	v_lshl_add_u64 v[136:137], v[26:27], 0, v[136:137]
	global_load_dwordx4 v[136:139], v[136:137], off nt
	v_add_u32_e32 v140, s4, v8
	v_ashrrev_i32_e32 v141, 31, v140
	v_lshlrev_b64 v[140:141], 13, v[140:141]
	v_lshl_add_u64 v[140:141], v[26:27], 0, v[140:141]
	global_load_dwordx4 v[140:143], v[140:141], off nt
	v_add_u32_e32 v144, s4, v9
	v_ashrrev_i32_e32 v145, 31, v144
	v_lshlrev_b64 v[144:145], 13, v[144:145]
	v_lshl_add_u64 v[144:145], v[26:27], 0, v[144:145]
	global_load_dwordx4 v[144:147], v[144:145], off nt
	v_lshl_add_u64 v[26:27], s[4:5], 1, v[4:5]
	v_lshl_add_u64 v[46:47], v[26:27], 0, v[46:47]
	s_waitcnt vmcnt(3)
	ds_write2_b32 v10, v20, v21 offset0:64 offset1:65
	ds_write2_b32 v10, v22, v23 offset0:66 offset1:67
	s_waitcnt vmcnt(2)
	ds_write2_b32 v11, v136, v137 offset1:1
	ds_write2_b32 v12, v138, v139 offset1:1
	s_waitcnt vmcnt(1)
	ds_write2_b32 v13, v140, v141 offset1:1
	ds_write2_b32 v14, v142, v143 offset1:1
	s_waitcnt vmcnt(0)
	ds_write2_b32 v15, v144, v145 offset1:1
	ds_write2_b32 v16, v146, v147 offset1:1
	s_waitcnt lgkmcnt(0)
	s_barrier
	ds_read2_b32 v[28:29], v17 offset0:64 offset1:96
	ds_read2_b32 v[30:31], v17 offset0:129 offset1:161
	ds_read2_b32 v[32:33], v17 offset0:194 offset1:226
	ds_read2_b32 v[34:35], v18 offset0:3 offset1:35
	ds_read2_b32 v[36:37], v18 offset0:68 offset1:100
	ds_read2_b32 v[38:39], v18 offset0:133 offset1:165
	ds_read2_b32 v[40:41], v18 offset0:198 offset1:230
	ds_read2_b32 v[42:43], v19 offset0:7 offset1:39
	s_waitcnt lgkmcnt(6)
	v_cvt_pk_bf16_f32 v20, v28, v30
	s_waitcnt lgkmcnt(4)
	v_cvt_pk_bf16_f32 v21, v32, v34
	s_waitcnt lgkmcnt(2)
	v_cvt_pk_bf16_f32 v22, v36, v38
	v_add_u32_e32 v28, 32, v44
	s_waitcnt lgkmcnt(0)
	v_cvt_pk_bf16_f32 v23, v40, v42
	global_store_dwordx4 v[46:47], v[20:23], off
	s_nop 1
	v_cvt_pk_bf16_f32 v20, v29, v31
	v_ashrrev_i32_e32 v29, 31, v28
	v_lshlrev_b64 v[28:29], 11, v[28:29]
	v_cvt_pk_bf16_f32 v21, v33, v35
	v_cvt_pk_bf16_f32 v22, v37, v39
	v_cvt_pk_bf16_f32 v23, v41, v43
	v_lshl_add_u64 v[26:27], v[26:27], 0, v[28:29]
	global_store_dwordx4 v[26:27], v[20:23], off
	s_cbranch_scc1 .LBB0_38
